# dead serialized LDS param reads removed; GEMM tile-top: DMA prologue issued before waiting on epilogue-constant load (vmcnt(8))
# speedup vs baseline: 1.0083x; 1.0045x over previous
.LBB0_102:
	s_waitcnt lgkmcnt(0)
	ds_read_b32 v0, v1
	ds_read_b32 v2, v1 offset:4
	s_cmp_lg_u32 s70, 0
	s_waitcnt lgkmcnt(0)
	v_readfirstlane_b32 s2, v0
	s_waitcnt lgkmcnt(0)
	ds_read_b32 v0, v1 offset:12
	v_readfirstlane_b32 s3, v2
	s_waitcnt lgkmcnt(0)
	ds_read_b32 v0, v1 offset:16
	ds_read_b32 v2, v1 offset:20
	s_waitcnt lgkmcnt(0)
	ds_read_b32 v3, v1 offset:32
	ds_read_b32 v4, v1 offset:36
	s_waitcnt lgkmcnt(0)
	ds_read_b32 v5, v1 offset:64
	v_readfirstlane_b32 s4, v0
	v_readfirstlane_b32 s5, v2
	ds_read_b32 v0, v1 offset:68
	s_waitcnt lgkmcnt(0)
	ds_read_b32 v2, v1 offset:172
	v_readfirstlane_b32 s6, v3
	v_readfirstlane_b32 s7, v4
	s_waitcnt lgkmcnt(0)
	ds_read_b32 v2, v1 offset:176
	ds_read_b32 v3, v1 offset:180
	ds_read_b32 v4, v1 offset:184
	v_readfirstlane_b32 s9, v0
	ds_read_b32 v0, v1 offset:188
	v_readfirstlane_b32 s8, v5
	s_waitcnt lgkmcnt(0)
	v_readfirstlane_b32 s12, v2
	v_readfirstlane_b32 s13, v3
	v_readfirstlane_b32 s10, v4
	v_readfirstlane_b32 s11, v0
	s_cbranch_scc1 .LBB0_203
	v_readlane_b32 s0, v254, 3
	v_readlane_b32 s1, v254, 4
	v_mov_b32_e32 v0, v201
	s_andn2_b64 vcc, exec, s[0:1]
	s_cbranch_vccnz .LBB0_158
	s_add_u32 s14, s10, 0x12c74000
	s_addc_u32 s15, s11, 0
	s_add_u32 s16, s10, 0x12b54000
	s_addc_u32 s17, s11, 0
	s_add_u32 s18, s10, 0x12b10000
	s_addc_u32 s19, s11, 0
	s_add_u32 s20, s10, 0x280000
	v_readlane_b32 s1, v254, 35
	v_ashrrev_i32_e32 v26, 8, v0
	s_mov_b32 s0, 0xd000
	s_addc_u32 s21, s11, 0
	v_mov_b32_e32 v0, s1
	v_mad_i32_i24 v27, v26, s0, v207
	s_add_u32 s22, s10, 0xa80000
	v_mad_i32_i24 v28, v26, s0, v0
	v_readlane_b32 s0, v254, 32
	s_addc_u32 s23, s11, 0
	v_readlane_b32 s28, v254, 0
	v_lshl_add_u32 v29, v26, 6, s0
	s_branch .LBB0_107

.LBB0_203:
	s_waitcnt lgkmcnt(0)
	ds_read_b32 v0, v1 offset:184
	ds_read_b32 v2, v1 offset:188
	v_mov_b32_e32 v200, v201
	s_mov_b32 s0, 0x1ffff0
	v_lshlrev_b32_e32 v3, 4, v200
	v_and_b32_e32 v4, 32, v200
	s_waitcnt lgkmcnt(0)
	v_readfirstlane_b32 s16, v0
	v_bitop3_b32 v4, v3, v4, 48 bitop3:0x6c
	v_add_u32_e32 v3, 0x2000, v3
	v_readfirstlane_b32 s17, v2
	s_add_u32 s37, s16, 0xa80000
	v_bfe_u32 v5, v200, 2, 4
	v_lshrrev_b32_e32 v6, 3, v200
	v_lshrrev_b32_e32 v3, 7, v3
	s_addc_u32 s56, s17, 0
	v_and_or_b32 v4, v200, 64, v4
	v_and_or_b32 v6, v6, s0, v5
	v_and_or_b32 v3, v3, s0, v5
	s_add_u32 s58, s16, 0x12c74000
	v_ashrrev_i32_e32 v0, 6, v200
	v_lshl_or_b32 v196, v6, 11, v4
	v_lshl_or_b32 v198, v3, 11, v4
	v_ashrrev_i32_e32 v3, 8, v200
	v_and_b32_e32 v4, 15, v200
	v_bfe_u32 v5, v200, 4, 2
	s_addc_u32 s59, s17, 0
	v_and_b32_e32 v2, 3, v0
	v_lshlrev_b32_e32 v7, 6, v4
	v_lshlrev_b32_e32 v8, 2, v200
	v_lshl_or_b32 v204, v3, 6, v4
	v_lshlrev_b32_e32 v4, 2, v5
	v_lshlrev_b32_e32 v6, 4, v5
	v_and_b32_e32 v8, 32, v8
	v_lshl_or_b32 v205, v2, 5, v4
	v_lshlrev_b32_e32 v4, 6, v200
	s_movk_i32 s6, 0x3c0
	s_add_u32 s18, s16, 0x12b10000
	s_mul_i32 s2, s70, 9
	v_lshlrev_b32_e32 v202, 10, v0
	v_lshlrev_b32_e32 v0, 12, v2
	v_bitop3_b32 v7, v6, v8, v7 bitop3:0x36
	v_lshlrev_b32_e32 v2, 13, v3
	v_and_or_b32 v4, v4, s6, v6
	s_movk_i32 s6, 0x400
	s_addc_u32 s19, s17, 0
	v_writelane_b32 v254, s2, 44
	v_cmp_eq_u32_e64 s[2:3], 1, v3
	v_add_u32_e32 v9, s33, v7
	v_add_u32_e32 v10, s52, v7
	v_add_u32_e32 v11, s53, v7
	v_add_u32_e32 v12, s34, v7
	v_add_u32_e32 v3, 0x400, v7
	v_xad_u32 v4, v4, v8, s6
	v_or_b32_e32 v5, 0x800, v2
	v_or_b32_e32 v6, 0x1000, v2
	v_or_b32_e32 v7, 0x1800, v2
	s_add_u32 s20, s16, 0x4e80000
	v_mov_b32_e32 v219, 0xc0
	v_mov_b32_e32 v218, 0xf00
	v_mov_b32_e32 v217, 0x80
	v_mov_b32_e32 v216, 0xf40
	v_mov_b32_e32 v215, 0xf80
	v_mov_b32_e32 v214, 3
	v_cmp_lt_i32_e64 s[0:1], s49, v200
	v_cmp_gt_u32_e64 s[4:5], s47, v200
	v_mov_b32_e32 v197, v1
	v_mov_b32_e32 v199, v1
	s_addc_u32 s21, s17, 0
	s_mov_b32 s71, 0
	v_add_u32_e32 v228, v9, v0
	v_add_u32_e32 v229, v3, v2
	v_add_u32_e32 v230, v4, v5
	v_add_u32_e32 v231, v4, v6
	v_add_u32_e32 v232, v4, v7
	v_add_u32_e32 v233, v10, v0
	v_add_u32_e32 v234, v11, v0
	v_add_u32_e32 v235, v12, v0
	s_branch .LBB0_207

.LBB0_220:
	s_andn2_saveexec_b64 s[8:9], s[8:9]
	v_add_u32_e32 v2, s22, v200
	v_ashrrev_i32_e32 v3, 31, v2
	v_lshl_add_u64 v[2:3], v[2:3], 2, s[18:19]
	s_or_b64 exec, exec, s[8:9]
	global_load_dword v0, v[2:3], off
	s_lshl_b32 s9, s71, 12
	s_ashr_i32 s25, s24, 31
	s_and_b32 s9, s9, 0x1000
	s_lshl_b64 s[10:11], s[24:25], 11
	s_add_i32 s25, s9, 0x400
	s_add_i32 s8, s24, 0x80
	s_add_i32 s25, s25, 0x20000
	s_add_u32 s44, s58, s10
	s_addc_u32 s45, s59, s11
	s_ashr_i32 s23, s22, 31
	s_lshl_b64 s[28:29], s[22:23], 11
	s_add_u32 s14, s37, s28
	v_add_u32_e32 v236, s33, v202
	s_addc_u32 s15, s56, s29
	s_ashr_i32 s9, s8, 31
	v_readfirstlane_b32 s40, v236
	v_add_u32_e32 v239, 0x2000, v236
	s_lshl_b64 s[30:31], s[8:9], 11
	v_add_u32_e32 v237, 0x400, v202
	v_readfirstlane_b32 s43, v239
	v_lshl_add_u32 v18, v200, 2, s25
	v_lshl_add_u64 v[2:3], s[44:45], 0, v[196:197]
	s_add_u32 s8, s58, s30
	s_mov_b32 m0, s40
	v_readfirstlane_b32 s41, v237
	v_add_u32_e32 v240, 0x2000, v237
	v_lshl_add_u64 v[4:5], s[44:45], 0, v[198:199]
	s_addc_u32 s9, s59, s31
	s_add_i32 s26, s22, 0x80
	v_add_u32_e32 v238, s52, v202
	v_readfirstlane_b32 s54, v240
	v_lshl_add_u64 v[6:7], s[14:15], 0, v[196:197]
	s_ashr_i32 s27, s26, 31
	v_readfirstlane_b32 s42, v238
	v_add_u32_e32 v241, 0x2000, v238
	v_lshl_add_u64 v[8:9], s[14:15], 0, v[198:199]
	s_lshl_b64 s[38:39], s[26:27], 11
	v_add_u32_e32 v242, 0x4000, v237
	v_readfirstlane_b32 s55, v241
	v_lshl_add_u64 v[10:11], s[8:9], 0, v[196:197]
	s_add_u32 s12, s37, s38
	v_add_u32_e32 v243, 0x6000, v237
	v_readfirstlane_b32 s72, v242
	v_lshl_add_u64 v[12:13], s[8:9], 0, v[198:199]
	s_addc_u32 s13, s56, s39
	v_readfirstlane_b32 s73, v243
	v_lshl_add_u64 v[14:15], s[12:13], 0, v[196:197]
	v_lshl_add_u64 v[16:17], s[12:13], 0, v[198:199]
	s_waitcnt lgkmcnt(0)
	global_load_lds_dwordx4 v[2:3], off
	s_mov_b32 m0, s43
	s_nop 0
	global_load_lds_dwordx4 v[4:5], off
	s_mov_b32 m0, s41
	s_nop 0
	global_load_lds_dwordx4 v[6:7], off
	s_mov_b32 m0, s54
	s_nop 0
	global_load_lds_dwordx4 v[8:9], off
	s_mov_b32 m0, s42
	s_nop 0
	global_load_lds_dwordx4 v[10:11], off
	s_mov_b32 m0, s55
	s_nop 0
	global_load_lds_dwordx4 v[12:13], off
	s_mov_b32 m0, s72
	s_nop 0
	global_load_lds_dwordx4 v[14:15], off
	s_mov_b32 m0, s73
	s_nop 0
	global_load_lds_dwordx4 v[16:17], off
	s_waitcnt vmcnt(8)
	ds_write_b32 v18, v0
	s_waitcnt lgkmcnt(0)
	s_barrier
	s_and_saveexec_b64 s[40:41], s[2:3]
	s_cbranch_execz .LBB0_224
	s_barrier

.LBB0_617:
	s_or_b64 exec, exec, s[38:39]
	s_waitcnt lgkmcnt(0)
	s_barrier
	s_waitcnt lgkmcnt(0)
	ds_read_b32 v0, v1 offset:72
	s_mov_b32 s71, s57
	s_lshl_b64 s[14:15], s[70:71], 2
	s_mov_b32 s19, s57
	s_waitcnt lgkmcnt(0)
	v_readfirstlane_b32 s0, v0
	ds_read_b32 v0, v1 offset:76
	s_waitcnt lgkmcnt(0)
	v_readfirstlane_b32 s1, v0
	ds_read_b32 v0, v1 offset:80
	s_waitcnt lgkmcnt(0)
	v_readfirstlane_b32 s2, v0
	ds_read_b32 v0, v1 offset:84
	s_waitcnt lgkmcnt(0)
	v_readfirstlane_b32 s3, v0
	ds_read_b32 v0, v1 offset:88
	v_writelane_b32 v254, s2, 45
	s_nop 1
	v_writelane_b32 v254, s3, 46
	s_waitcnt lgkmcnt(0)
	v_readfirstlane_b32 s2, v0
	ds_read_b32 v0, v1 offset:92
	s_waitcnt lgkmcnt(0)
	v_readfirstlane_b32 s3, v0
	s_waitcnt lgkmcnt(0)
	ds_read_b32 v0, v1 offset:104
	v_writelane_b32 v254, s2, 47
	s_nop 1
	v_writelane_b32 v254, s3, 48
	s_waitcnt lgkmcnt(0)
	v_readfirstlane_b32 s2, v0
	ds_read_b32 v0, v1 offset:108
	s_waitcnt lgkmcnt(0)
	v_readfirstlane_b32 s3, v0
	ds_read_b32 v0, v1 offset:112
	s_waitcnt lgkmcnt(0)
	v_readfirstlane_b32 s4, v0
	ds_read_b32 v0, v1 offset:116
	s_waitcnt lgkmcnt(0)
	v_readfirstlane_b32 s5, v0
	ds_read_b32 v0, v1 offset:120
	s_waitcnt lgkmcnt(0)
	v_readfirstlane_b32 s37, v0
	ds_read_b32 v0, v1 offset:124
	s_waitcnt lgkmcnt(0)
	v_readfirstlane_b32 s8, v0
	ds_read_b32 v0, v1 offset:128
	s_waitcnt lgkmcnt(0)
	v_readfirstlane_b32 s9, v0
	ds_read_b32 v0, v1 offset:132
	s_waitcnt lgkmcnt(0)
	v_readfirstlane_b32 s10, v0
	s_waitcnt lgkmcnt(0)
	ds_read_b32 v0, v1 offset:184
	s_waitcnt lgkmcnt(0)
	v_readfirstlane_b32 s12, v0
	ds_read_b32 v0, v1 offset:188
	s_add_u32 s6, s12, s14
	v_writelane_b32 v254, s14, 49
	s_waitcnt lgkmcnt(0)
	v_readfirstlane_b32 s13, v0
	s_addc_u32 s7, s13, s15
	v_writelane_b32 v254, s15, 50
	s_add_u32 s14, s6, 0x244020
	s_addc_u32 s15, s7, 0
	s_lshl_b32 s18, s70, 6
	s_lshl_b32 s7, s70, 3
	s_add_u32 s20, s12, 0x4e80000
	s_addc_u32 s21, s13, 0
	s_lshl_b64 s[16:17], s[18:19], 2
	s_add_u32 s22, s2, s16
	s_addc_u32 s23, s3, s17
	s_add_u32 s24, s12, 0x100000
	s_addc_u32 s25, s13, 0
	s_add_u32 s26, s12, 0x180000
	s_addc_u32 s27, s13, 0
	s_add_u32 s28, s12, 0xa80000
	s_addc_u32 s29, s13, 0
	v_writelane_b32 v254, s7, 51
	s_add_u32 s30, s4, s16
	v_writelane_b32 v254, s16, 53
	s_addc_u32 s31, s5, s17
	s_add_u32 s92, s12, 0x3d80000
	s_addc_u32 s93, s13, 0
	s_add_u32 s96, s12, 0x10890000
	s_mul_i32 s6, s70, 0x2400
	s_addc_u32 s97, s13, 0
	s_add_u32 s40, s0, s6
	s_addc_u32 s41, s1, 0
	s_add_u32 s0, s12, 0x1f490000
	s_addc_u32 s1, s13, 0
	v_writelane_b32 v254, s17, 54
	s_add_u32 s16, s12, 0x14a90000
	s_addc_u32 s17, s13, 0
	v_writelane_b32 v254, s0, 55
	s_add_u32 s38, s12, 0x200040
	s_addc_u32 s39, s13, 0
	v_writelane_b32 v254, s1, 56
	s_branch .LBB0_621

.LBB0_1166:
	s_or_b64 exec, exec, s[16:17]
	s_waitcnt lgkmcnt(0)
	s_barrier
	s_waitcnt lgkmcnt(0)
	ds_read_b32 v0, v1 offset:64
	s_mul_i32 s14, s70, 0xb00000
	s_mul_hi_u32 s15, s70, 0xb00000
	s_mul_i32 s21, s70, 0x31800
	s_mul_hi_u32 s20, s70, 0x31800
	s_waitcnt lgkmcnt(0)
	v_readfirstlane_b32 s2, v0
	ds_read_b32 v0, v1 offset:68
	s_waitcnt lgkmcnt(0)
	v_readfirstlane_b32 s3, v0
	s_waitcnt lgkmcnt(0)
	ds_read_b32 v0, v1 offset:136
	s_waitcnt lgkmcnt(0)
	v_readfirstlane_b32 s8, v0
	ds_read_b32 v0, v1 offset:140
	s_waitcnt lgkmcnt(0)
	v_readfirstlane_b32 s9, v0
	ds_read_b32 v0, v1 offset:144
	s_waitcnt lgkmcnt(0)
	v_readfirstlane_b32 s4, v0
	ds_read_b32 v0, v1 offset:148
	s_waitcnt lgkmcnt(0)
	v_readfirstlane_b32 s5, v0
	ds_read_b32 v0, v1 offset:152
	s_waitcnt lgkmcnt(0)
	v_readfirstlane_b32 s0, v0
	ds_read_b32 v0, v1 offset:156
	s_nop 0
	v_writelane_b32 v254, s0, 57
	s_waitcnt lgkmcnt(0)
	v_readfirstlane_b32 s0, v0
	ds_read_b32 v0, v1 offset:160
	s_nop 0
	v_writelane_b32 v254, s0, 58
	s_waitcnt lgkmcnt(0)
	v_readfirstlane_b32 s0, v0
	ds_read_b32 v0, v1 offset:164
	s_nop 0
	v_writelane_b32 v254, s0, 59
	s_waitcnt lgkmcnt(0)
	v_readfirstlane_b32 s0, v0
	ds_read_b32 v0, v1 offset:168
	s_nop 0
	v_writelane_b32 v254, s0, 60
	s_waitcnt lgkmcnt(0)
	v_readfirstlane_b32 s6, v0
	ds_read_b32 v0, v1 offset:172
	v_readlane_b32 s0, v254, 49
	v_readlane_b32 s1, v254, 50
	s_waitcnt lgkmcnt(0)
	v_readfirstlane_b32 s7, v0
	s_waitcnt lgkmcnt(0)
	ds_read_b32 v0, v1 offset:184
	s_waitcnt lgkmcnt(0)
	v_readfirstlane_b32 s10, v0
	ds_read_b32 v0, v1 offset:188
	s_add_u32 s0, s10, s0
	s_waitcnt lgkmcnt(0)
	v_readfirstlane_b32 s11, v0
	s_addc_u32 s1, s11, s1
	s_add_u32 s12, s0, 0x244000
	s_addc_u32 s13, s1, 0
	s_cmp_lg_u32 s70, 3
	s_cselect_b64 s[92:93], -1, 0
	s_cmp_eq_u32 s70, 3
	s_cselect_b64 s[0:1], -1, 0
	v_writelane_b32 v254, s0, 55
	s_nop 1
	v_writelane_b32 v254, s1, 56
	s_and_b64 s[0:1], s[0:1], exec
	s_cselect_b32 s1, 0, 64
	s_cselect_b32 s0, 0, 0x140
	s_add_i32 s24, s1, s0
	s_add_i32 s0, s70, 1
	v_writelane_b32 v254, s1, 61
	s_addk_i32 s24, 0x948
	s_mul_hi_u32 s16, s0, 0x910000
	s_mul_i32 s17, s0, 0x910000
	s_mul_hi_u32 s18, s0, 0x16800
	s_mov_b32 s91, s0
	s_mul_i32 s19, s0, 0x16800
	s_lshl_b64 s[0:1], s[70:71], 22
	s_lshl_b32 s22, s70, 2
	s_add_u32 s2, s2, s17
	v_writelane_b32 v254, s22, 62
	s_addc_u32 s3, s3, s16
	v_writelane_b32 v254, s2, 63
	s_nop 1
	v_writelane_b32 v255, s3, 0
	s_add_u32 s2, s10, 0x12c74000
	s_addc_u32 s3, s11, 0
	v_writelane_b32 v255, s2, 1
	s_nop 1
	v_writelane_b32 v255, s3, 2
	s_add_u32 s2, s10, s19
	s_addc_u32 s3, s11, s18
	s_add_u32 s2, s2, 0x12b54000
	s_addc_u32 s3, s3, 0
	v_writelane_b32 v255, s2, 3
	s_nop 1
	v_writelane_b32 v255, s3, 4
	s_add_u32 s2, s6, s14
	s_addc_u32 s3, s7, s15
	v_writelane_b32 v255, s2, 5
	s_nop 1
	v_writelane_b32 v255, s3, 6
	s_add_u32 s2, s10, 0x13e74000
	s_addc_u32 s3, s11, 0
	v_writelane_b32 v255, s2, 7
	s_nop 1
	v_writelane_b32 v255, s3, 8
	s_add_u32 s2, s10, 0x13374000
	s_addc_u32 s3, s11, 0
	v_writelane_b32 v255, s2, 9
	s_nop 1
	v_writelane_b32 v255, s3, 10
	s_add_u32 s2, s10, s21
	s_addc_u32 s3, s11, s20
	s_add_u32 s2, s2, 0x12bae000
	s_addc_u32 s3, s3, 0
	s_add_u32 s30, s4, s0
	s_addc_u32 s31, s5, s1
	s_add_u32 s40, s10, 0x13174000
	s_addc_u32 s41, s11, 0
	s_add_u32 s42, s10, 0xa80000
	s_addc_u32 s43, s11, 0
	s_add_u32 s58, s10, 0x2c80000
	s_addc_u32 s59, s11, 0
	s_add_u32 s44, s10, 0x3d80000
	s_addc_u32 s45, s11, 0
	s_add_u32 s54, s10, 0x4e80000
	s_addc_u32 s55, s11, 0
	s_add_u32 s72, s10, 0x4e80400
	s_addc_u32 s73, s11, 0
	s_add_u32 s74, s10, 0x4e80200
	s_addc_u32 s75, s11, 0
	s_add_u32 s76, s10, 0x204000
	s_addc_u32 s77, s11, 0
	s_add_u32 s0, s10, 0x10890000
	v_writelane_b32 v254, s0, 45
	s_addc_u32 s0, s11, 0
	s_add_u32 s71, s10, 0x10a90000
	s_addc_u32 s25, s11, 0
	s_add_u32 s20, s10, 0xe890000
	s_addc_u32 s21, s11, 0
	s_add_u32 s94, s10, 0x14a90000
	s_addc_u32 s95, s11, 0
	s_add_u32 s16, s10, 0x1f490000
	s_addc_u32 s17, s11, 0
	v_writelane_b32 v254, s0, 47
	s_add_u32 s18, s10, 0x9280000
	s_addc_u32 s19, s11, 0
	v_readlane_b32 s0, v254, 38
	v_writelane_b32 v255, s2, 11
	v_readlane_b32 s1, v254, 39
	s_add_u32 s0, s10, s0
	v_writelane_b32 v255, s3, 12
	s_addc_u32 s1, s11, s1
	v_writelane_b32 v255, s0, 13
	s_nop 1
	v_writelane_b32 v255, s1, 14
	v_readlane_b32 s0, v254, 40
	v_readlane_b32 s1, v254, 41
	s_add_u32 s0, s10, s0
	s_addc_u32 s1, s11, s1
	v_writelane_b32 v255, s0, 15
	s_nop 1
	v_writelane_b32 v255, s1, 16
	s_add_u32 s0, s10, 0x10890080
	v_writelane_b32 v254, s0, 51
	s_addc_u32 s0, s11, 0
	s_add_u32 s26, s10, 0xe890080
	s_addc_u32 s27, s11, 0
	s_add_u32 s28, s10, 0x10a90080
	v_writelane_b32 v254, s0, 49
	s_addc_u32 s29, s11, 0
	s_branch .LBB0_1171

.LBB0_1356:
	s_or_b64 exec, exec, s[16:17]
	s_waitcnt lgkmcnt(0)
	s_barrier
	s_waitcnt lgkmcnt(0)
	ds_read_b32 v0, v1 offset:96
	v_readlane_b32 s0, v254, 8
	v_readlane_b32 s1, v254, 9
	s_andn2_b64 vcc, exec, s[0:1]
	s_waitcnt lgkmcnt(0)
	v_readfirstlane_b32 s2, v0
	ds_read_b32 v0, v1 offset:100
	s_waitcnt lgkmcnt(0)
	v_readfirstlane_b32 s3, v0
	s_waitcnt lgkmcnt(0)
	ds_read_b32 v0, v1 offset:184
	s_waitcnt lgkmcnt(0)
	v_readfirstlane_b32 s14, v0
	ds_read_b32 v0, v1 offset:188
	s_waitcnt lgkmcnt(0)
	v_readfirstlane_b32 s15, v0
	v_mov_b32_e32 v0, v201
	s_cbranch_vccnz .LBB0_1361
	s_add_u32 s0, s14, 0x9280000
	s_addc_u32 s1, s15, 0
	v_readlane_b32 s4, v254, 53
	v_readlane_b32 s5, v254, 54
	s_add_u32 s2, s2, s4
	s_addc_u32 s3, s3, s5
	s_add_u32 s4, s14, 0xd790000
	s_addc_u32 s5, s15, 0
	s_add_u32 s6, s14, 0x4e80000
	s_addc_u32 s7, s15, 0
	s_add_u32 s8, s14, 0x12b10000
	v_ashrrev_i32_e32 v0, 6, v0
	s_addc_u32 s9, s15, 0
	v_and_b32_e32 v0, -4, v0
	s_add_u32 s10, s14, 0x12b32000
	v_readlane_b32 s12, v254, 33
	s_addc_u32 s11, s15, 0
	v_readlane_b32 s16, v254, 0
	v_add_u32_e32 v4, s12, v0
	s_branch .LBB0_1359

.LBB0_1405:
	s_or_b64 exec, exec, s[16:17]
	s_waitcnt lgkmcnt(0)
	s_barrier
	s_waitcnt lgkmcnt(0)
	ds_read_b32 v0, v1 offset:40
	v_readlane_b32 s0, v254, 55
	v_readlane_b32 s1, v254, 56
	v_mov_b32_e32 v228, v201
	s_movk_i32 s8, 0x3c0
	s_waitcnt lgkmcnt(0)
	v_readfirstlane_b32 s14, v0
	ds_read_b32 v0, v1 offset:44
	s_waitcnt lgkmcnt(0)
	ds_read_b32 v2, v1 offset:176
	ds_read_b32 v3, v1 offset:180
	ds_read_b32 v4, v1 offset:184
	ds_read_b32 v5, v1 offset:188
	v_readlane_b32 s25, v254, 25
	s_waitcnt lgkmcnt(0)
	v_readfirstlane_b32 s13, v3
	v_readfirstlane_b32 s10, v4
	v_readfirstlane_b32 s11, v5
	s_add_u32 s77, s10, 0x4e80000
	s_addc_u32 s94, s11, 0
	s_add_u32 s95, s10, 0x13174000
	s_addc_u32 s91, s11, 0
	s_and_b64 s[0:1], s[0:1], exec
	v_lshlrev_b32_e32 v3, 4, v228
	v_and_b32_e32 v4, 32, v228
	s_movk_i32 s0, 0x88
	v_bitop3_b32 v4, v3, v4, 48 bitop3:0x6c
	v_add_u32_e32 v3, 0x2000, v3
	s_cselect_b32 s76, 0x80, s0
	v_bfe_u32 v5, v228, 2, 4
	v_lshrrev_b32_e32 v6, 3, v228
	s_mov_b32 s0, 0x1ffff0
	v_lshrrev_b32_e32 v3, 7, v3
	v_and_or_b32 v4, v228, 64, v4
	v_and_or_b32 v6, v6, s0, v5
	v_and_or_b32 v3, v3, s0, v5
	v_lshl_or_b32 v196, v6, 11, v4
	v_lshl_or_b32 v198, v3, 11, v4
	v_ashrrev_i32_e32 v3, 8, v228
	v_and_b32_e32 v4, 15, v228
	v_bfe_u32 v5, v228, 4, 2
	s_lshr_b32 s22, s76, 1
	v_readlane_b32 s0, v254, 14
	v_lshlrev_b32_e32 v6, 4, v5
	v_lshlrev_b32_e32 v7, 6, v4
	v_lshlrev_b32_e32 v8, 2, v228
	v_lshl_or_b32 v230, v3, 6, v4
	v_lshlrev_b32_e32 v4, 6, v228
	s_mul_i32 s0, s22, s0
	s_lshl_b32 s56, s70, 10
	v_and_b32_e32 v8, 32, v8
	v_and_or_b32 v4, v4, s8, v6
	s_movk_i32 s8, 0x400
	s_add_i32 s0, s0, s25
	v_xad_u32 v4, v4, v8, s8
	s_lshl_b64 s[8:9], s[56:57], 2
	v_readfirstlane_b32 s15, v0
	s_add_u32 s14, s14, s8
	s_addc_u32 s15, s15, s9
	s_add_u32 s16, s10, 0x280000
	v_writelane_b32 v254, s0, 45
	s_addc_u32 s17, s11, 0
	s_add_u32 s18, s10, 0xa80000
	v_readlane_b32 s8, v254, 23
	s_addc_u32 s19, s11, 0
	s_mul_hi_u32 s8, s22, s8
	s_add_u32 s20, s10, 0x12b32000
	s_mul_i32 s9, s8, s67
	s_addc_u32 s21, s11, 0
	s_sub_i32 s9, s22, s9
	s_add_i32 s23, s8, 1
	s_sub_i32 s24, s9, s67
	s_cmp_ge_u32 s9, s67
	s_cselect_b32 s8, s23, s8
	s_cselect_b32 s9, s24, s9
	s_add_i32 s23, s8, 1
	s_cmp_ge_u32 s9, s67
	s_cselect_b32 s74, s23, s8
	s_mul_i32 s75, s74, s67
	s_sub_i32 s8, s22, s75
	s_cmp_gt_i32 s8, 0
	v_ashrrev_i32_e32 v0, 6, v228
	s_cselect_b64 s[22:23], -1, 0
	v_readfirstlane_b32 s12, v2
	v_and_b32_e32 v2, 3, v0
	v_writelane_b32 v254, s22, 47
	s_cmp_lt_u32 s25, s8
	v_lshlrev_b32_e32 v229, 10, v0
	v_lshlrev_b32_e32 v0, 12, v2
	v_bitop3_b32 v7, v6, v8, v7 bitop3:0x36
	v_lshlrev_b32_e32 v200, 5, v2
	v_lshlrev_b32_e32 v2, 13, v3
	v_writelane_b32 v254, s23, 48
	s_cselect_b64 s[8:9], -1, 0
	v_cmp_eq_u32_e64 s[2:3], 1, v3
	v_add_u32_e32 v9, s33, v7
	v_add_u32_e32 v10, s52, v7
	v_add_u32_e32 v11, s53, v7
	v_add_u32_e32 v12, s34, v7
	v_lshlrev_b32_e32 v202, 2, v5
	v_cmp_eq_u32_e64 s[6:7], 0, v5
	v_add_u32_e32 v3, 0x400, v7
	v_or_b32_e32 v5, 0x800, v2
	v_or_b32_e32 v6, 0x1000, v2
	v_or_b32_e32 v7, 0x1800, v2
	v_writelane_b32 v254, s8, 51
	v_cmp_lt_i32_e64 s[0:1], s49, v228
	v_cmp_gt_u32_e64 s[4:5], s47, v228
	s_mov_b32 s96, 0
	v_or_b32_e32 v204, v200, v202
	v_mov_b32_e32 v197, v1
	v_mov_b32_e32 v199, v1
	v_writelane_b32 v254, s9, 52
	v_mov_b32_e32 v205, v1
	v_add_u32_e32 v231, v9, v0
	v_add_u32_e32 v232, v3, v2
	v_add_u32_e32 v233, v4, v5
	v_add_u32_e32 v234, v4, v6
	v_add_u32_e32 v235, v4, v7
	v_add_u32_e32 v236, v10, v0
	v_add_u32_e32 v237, v11, v0
	v_add_u32_e32 v238, v12, v0
	s_branch .LBB0_1409

.LBB0_1430:
	s_mul_hi_i32 s8, s24, 0x78787879
	s_lshr_b32 s9, s8, 31
	s_ashr_i32 s8, s8, 11
	s_add_i32 s8, s8, s9
	s_mul_i32 s9, s8, 0xffffef00
	s_add_i32 s9, s9, s24
	s_cmpk_gt_i32 s9, 0xff
	s_cselect_b32 s8, s8, 8
	v_readlane_b32 s9, v254, 44
	s_add_i32 s8, s8, s9
	s_mul_hi_i32 s9, s8, 0x6000
	s_mulk_i32 s8, 0x6000
	s_add_u32 s8, s10, s8
	s_waitcnt lgkmcnt(0)
	v_add_u32_sdwa v2, s22, v228 dst_sel:DWORD dst_unused:UNUSED_PAD src0_sel:DWORD src1_sel:BYTE_0
	s_addc_u32 s9, s11, s9
	v_ashrrev_i32_e32 v3, 31, v2
	s_and_saveexec_b64 s[28:29], s[0:1]
	s_xor_b64 s[28:29], exec, s[28:29]
	s_cbranch_execz .LBB0_1432
	v_lshlrev_b64 v[2:3], 2, v[2:3]
	v_lshl_add_u64 v[4:5], s[14:15], 0, v[2:3]
	v_lshl_add_u64 v[2:3], s[8:9], 0, v[2:3]
	v_add_co_u32_e32 v2, vcc, 0x4000, v2
	global_load_dword v0, v[4:5], off
	s_nop 0
	v_addc_co_u32_e32 v3, vcc, 0, v3, vcc
	global_load_dword v6, v[2:3], off
.LBB0_1432:
	s_andn2_saveexec_b64 s[28:29], s[28:29]
	s_cbranch_execz .LBB0_1434
	v_lshl_add_u64 v[2:3], v[2:3], 2, s[8:9]
	v_add_co_u32_e32 v2, vcc, 0x2000, v2
	s_nop 1
	v_addc_co_u32_e32 v3, vcc, 0, v3, vcc
	global_load_dword v0, v[2:3], off
	v_mov_b32_e32 v6, 0
.LBB0_1434:
	s_or_b64 exec, exec, s[28:29]
	s_lshl_b32 s8, s96, 12
	s_and_b32 s8, s8, 0x1000
	s_add_i32 s56, s8, 0x400
	s_ashr_i32 s23, s22, 31
	s_add_i32 s56, s56, 0x20000
	s_lshl_b64 s[28:29], s[22:23], 11
	s_add_u32 s8, s95, s28
	v_add_u32_e32 v239, s33, v229
	v_lshl_add_u32 v7, v228, 2, s56
	s_addc_u32 s9, s91, s29
	v_readfirstlane_b32 s25, v239
	v_add_u32_e32 v240, 0x2000, v239
	s_waitcnt lgkmcnt(0)
	v_lshl_add_u64 v[2:3], s[8:9], 0, v[196:197]
	s_mov_b32 m0, s25
	v_readfirstlane_b32 s25, v240
	global_load_lds_dwordx4 v[2:3], off
	s_mov_b32 m0, s25
	s_ashr_i32 s25, s24, 31
	s_lshl_b64 s[30:31], s[24:25], 11
	s_add_u32 s54, s77, s30
	s_addc_u32 s55, s94, s31
	s_add_i32 s38, s22, 0x80
	s_ashr_i32 s39, s38, 31
	s_lshl_b64 s[40:41], s[38:39], 11
	v_add_u32_e32 v241, 0x400, v229
	s_add_u32 s70, s95, s40
	v_lshl_add_u64 v[2:3], s[8:9], 0, v[198:199]
	v_readfirstlane_b32 s25, v241
	v_add_u32_e32 v242, 0x2000, v241
	s_addc_u32 s71, s91, s41
	s_add_i32 s38, s24, 0x80
	global_load_lds_dwordx4 v[2:3], off
	v_lshl_add_u64 v[2:3], s[54:55], 0, v[196:197]
	s_mov_b32 m0, s25
	v_readfirstlane_b32 s25, v242
	v_add_u32_e32 v243, s52, v229
	s_ashr_i32 s39, s38, 31
	global_load_lds_dwordx4 v[2:3], off
	v_lshl_add_u64 v[2:3], s[54:55], 0, v[198:199]
	s_mov_b32 m0, s25
	v_readfirstlane_b32 s25, v243
	v_add_u32_e32 v244, 0x2000, v243
	s_lshl_b64 s[44:45], s[38:39], 11
	global_load_lds_dwordx4 v[2:3], off
	v_lshl_add_u64 v[2:3], s[70:71], 0, v[196:197]
	s_mov_b32 m0, s25
	v_readfirstlane_b32 s25, v244
	s_add_u32 s42, s77, s44
	v_add_u32_e32 v245, 0x4000, v241
	global_load_lds_dwordx4 v[2:3], off
	v_lshl_add_u64 v[2:3], s[70:71], 0, v[198:199]
	s_mov_b32 m0, s25
	s_addc_u32 s43, s94, s45
	v_readfirstlane_b32 s25, v245
	v_add_u32_e32 v246, 0x6000, v241
	global_load_lds_dwordx4 v[2:3], off
	v_lshl_add_u64 v[2:3], s[42:43], 0, v[196:197]
	s_mov_b32 m0, s25
	v_readfirstlane_b32 s25, v246
	global_load_lds_dwordx4 v[2:3], off
	v_lshl_add_u64 v[2:3], s[42:43], 0, v[198:199]
	s_mov_b32 m0, s25
	s_nop 0
	global_load_lds_dwordx4 v[2:3], off
	s_waitcnt vmcnt(8)
	v_add_f32_e32 v6, 1.0, v6
	v_mul_f32_e32 v0, v0, v6
	ds_write_b32 v7, v0 offset:1024
	s_waitcnt lgkmcnt(0)
	s_barrier
	s_and_saveexec_b64 s[58:59], s[2:3]
	s_cbranch_execz .LBB0_1436
	s_barrier

.LBB0_1545:
	s_or_b64 exec, exec, s[16:17]
	s_waitcnt lgkmcnt(0)
	s_barrier
	s_waitcnt lgkmcnt(0)
	ds_read_b32 v0, v1 offset:184
	ds_read_b32 v2, v1 offset:188
	v_mov_b32_e32 v134, v201
	s_mov_b32 s0, 0x1ffff0
	s_waitcnt lgkmcnt(0)
	v_readfirstlane_b32 s6, v0
	v_lshlrev_b32_e32 v4, 4, v134
	v_and_b32_e32 v0, 32, v134
	v_readfirstlane_b32 s7, v2
	s_add_u32 s42, s6, 0xa80000
	v_bitop3_b32 v0, v4, v0, 48 bitop3:0x6c
	v_add_u32_e32 v4, 0x2000, v4
	s_addc_u32 s43, s7, 0
	v_bfe_u32 v5, v134, 2, 4
	v_and_or_b32 v6, v134, 64, v0
	v_lshrrev_b32_e32 v0, 3, v134
	v_lshrrev_b32_e32 v4, 7, v4
	s_add_u32 s44, s6, 0x13374000
	v_and_or_b32 v0, v0, s0, v5
	v_and_or_b32 v4, v4, s0, v5
	s_mul_i32 s0, s76, 22
	s_addc_u32 s45, s7, 0
	s_lshr_b32 s0, s0, 3
	v_readlane_b32 s1, v254, 23
	s_mul_hi_u32 s1, s0, s1
	s_mul_i32 s2, s1, s67
	s_sub_i32 s2, s0, s2
	s_add_i32 s3, s1, 1
	s_sub_i32 s4, s2, s67
	s_cmp_ge_u32 s2, s67
	s_cselect_b32 s1, s3, s1
	s_cselect_b32 s2, s4, s2
	s_add_i32 s3, s1, 1
	s_cmp_ge_u32 s2, s67
	s_cselect_b32 s54, s3, s1
	s_mul_i32 s55, s54, s67
	s_sub_i32 s1, s0, s55
	s_cmp_gt_i32 s1, 0
	v_readlane_b32 s2, v254, 25
	v_lshl_or_b32 v0, v0, 11, v6
	v_lshl_or_b32 v130, v4, 11, v6
	v_ashrrev_i32_e32 v4, 8, v134
	v_and_b32_e32 v5, 15, v134
	v_bfe_u32 v6, v134, 4, 2
	s_cselect_b64 s[8:9], -1, 0
	s_cmp_lt_u32 s2, s1
	v_readlane_b32 s1, v254, 14
	s_mul_i32 s58, s0, s1
	v_lshlrev_b32_e32 v7, 4, v6
	v_lshlrev_b32_e32 v8, 6, v5
	v_lshlrev_b32_e32 v9, 2, v134
	v_lshl_or_b32 v136, v4, 6, v5
	v_lshlrev_b32_e32 v5, 6, v134
	s_movk_i32 s12, 0x3c0
	v_ashrrev_i32_e32 v2, 6, v134
	s_cselect_b64 s[10:11], -1, 0
	s_add_i32 s58, s58, s2
	v_and_b32_e32 v9, 32, v9
	v_and_or_b32 v5, v5, s12, v7
	s_movk_i32 s12, 0x400
	v_and_b32_e32 v3, 3, v2
	v_xad_u32 v5, v5, v9, s12
	s_add_u32 s12, s6, 0x12b32000
	v_lshlrev_b32_e32 v135, 10, v2
	v_lshlrev_b32_e32 v2, 12, v3
	v_bitop3_b32 v8, v7, v9, v8 bitop3:0x36
	v_lshlrev_b32_e32 v137, 5, v3
	v_lshlrev_b32_e32 v3, 13, v4
	s_addc_u32 s13, s7, 0
	v_cmp_eq_u32_e64 s[2:3], 1, v4
	v_add_u32_e32 v10, s33, v8
	v_add_u32_e32 v11, s52, v8
	v_add_u32_e32 v12, s53, v8
	v_add_u32_e32 v13, s34, v8
	v_lshlrev_b32_e32 v138, 2, v6
	v_add_u32_e32 v4, 0x400, v8
	v_or_b32_e32 v6, 0x800, v3
	v_or_b32_e32 v7, 0x1000, v3
	v_or_b32_e32 v8, 0x1800, v3
	s_add_u32 s14, s6, 0x4e80000
	s_mov_b32 s56, 0
	v_cmp_lt_i32_e64 s[0:1], s49, v134
	v_cmp_gt_u32_e64 s[4:5], s47, v134
	v_mov_b32_e32 v131, v1
	s_addc_u32 s15, s7, 0
	v_add_u32_e32 v139, v10, v2
	v_add_u32_e32 v140, v4, v3
	v_add_u32_e32 v141, v5, v6
	v_add_u32_e32 v142, v5, v7
	v_add_u32_e32 v143, v5, v8
	v_add_u32_e32 v144, v11, v2
	v_add_u32_e32 v145, v12, v2
	v_add_u32_e32 v146, v13, v2
	s_branch .LBB0_1548

.LBB0_1557:
	s_andn2_saveexec_b64 s[20:21], s[20:21]
	v_add_u32_e32 v2, s16, v134
	v_ashrrev_i32_e32 v3, 31, v2
	v_lshl_add_u64 v[2:3], v[2:3], 2, s[12:13]
	s_or_b64 exec, exec, s[20:21]
	global_load_dword v4, v[2:3], off
	s_lshl_b32 s17, s56, 12
	s_and_b32 s17, s17, 0x1000
	s_add_i32 s59, s17, 0x400
	s_ashr_i32 s19, s18, 31
	s_add_i32 s59, s59, 0x20000
	s_lshl_b64 s[20:21], s[18:19], 11
	s_add_u32 s26, s44, s20
	v_add_u32_e32 v132, s33, v135
	v_lshl_add_u32 v5, v134, 2, s59
	s_addc_u32 s27, s45, s21
	v_readfirstlane_b32 s17, v132
	v_add_u32_e32 v133, 0x2000, v132
	s_mov_b32 m0, s17
	v_readfirstlane_b32 s17, v133
	v_add_u32_e32 v147, 0x400, v135
	v_add_u32_e32 v148, 0x2000, v147
	v_add_u32_e32 v149, s52, v135
	v_add_u32_e32 v150, 0x2000, v149
	v_add_u32_e32 v151, 0x4000, v147
	v_add_u32_e32 v152, 0x6000, v147
	s_waitcnt lgkmcnt(0)
	v_lshl_add_u64 v[2:3], s[26:27], 0, v[0:1]
	global_load_lds_dwordx4 v[2:3], off
	s_mov_b32 m0, s17
	s_ashr_i32 s17, s16, 31
	s_lshl_b64 s[22:23], s[16:17], 11
	s_add_u32 s28, s42, s22
	s_addc_u32 s29, s43, s23
	s_or_b32 s24, s18, 0x80
	s_ashr_i32 s25, s24, 31
	s_lshl_b64 s[24:25], s[24:25], 11
	s_add_u32 s30, s44, s24
	v_lshl_add_u64 v[2:3], s[26:27], 0, v[130:131]
	v_readfirstlane_b32 s17, v147
	s_addc_u32 s31, s45, s25
	s_or_b32 s24, s16, 0x80
	global_load_lds_dwordx4 v[2:3], off
	v_lshl_add_u64 v[2:3], s[28:29], 0, v[0:1]
	s_mov_b32 m0, s17
	v_readfirstlane_b32 s17, v148
	s_ashr_i32 s25, s24, 31
	global_load_lds_dwordx4 v[2:3], off
	v_lshl_add_u64 v[2:3], s[28:29], 0, v[130:131]
	s_mov_b32 m0, s17
	v_readfirstlane_b32 s17, v149
	s_lshl_b64 s[24:25], s[24:25], 11
	global_load_lds_dwordx4 v[2:3], off
	v_lshl_add_u64 v[2:3], s[30:31], 0, v[0:1]
	s_mov_b32 m0, s17
	v_readfirstlane_b32 s17, v150
	s_add_u32 s24, s42, s24
	global_load_lds_dwordx4 v[2:3], off
	v_lshl_add_u64 v[2:3], s[30:31], 0, v[130:131]
	s_mov_b32 m0, s17
	s_addc_u32 s25, s43, s25
	v_readfirstlane_b32 s17, v151
	global_load_lds_dwordx4 v[2:3], off
	v_lshl_add_u64 v[2:3], s[24:25], 0, v[0:1]
	s_mov_b32 m0, s17
	v_readfirstlane_b32 s17, v152
	global_load_lds_dwordx4 v[2:3], off
	v_lshl_add_u64 v[2:3], s[24:25], 0, v[130:131]
	s_mov_b32 m0, s17
	s_nop 0
	global_load_lds_dwordx4 v[2:3], off
	s_waitcnt vmcnt(8)
	ds_write_b32 v5, v4
	s_waitcnt lgkmcnt(0)
	s_barrier
	s_and_saveexec_b64 s[40:41], s[2:3]
	s_cbranch_execz .LBB0_1561
	s_barrier

.LBB0_1609:
	s_or_b64 exec, exec, s[16:17]
	s_waitcnt lgkmcnt(0)
	s_barrier
	s_waitcnt lgkmcnt(0)
	ds_read_b32 v0, v1 offset:32
	v_mov_b32_e32 v205, v201
	s_mov_b32 s0, 0xfffff0
	s_movk_i32 s8, 0x3c0
	s_mov_b32 s54, 0
	s_waitcnt lgkmcnt(0)
	v_readfirstlane_b32 s10, v0
	ds_read_b32 v0, v1 offset:36
	s_waitcnt lgkmcnt(0)
	ds_read_b32 v2, v1 offset:176
	ds_read_b32 v3, v1 offset:180
	ds_read_b32 v4, v1 offset:184
	ds_read_b32 v5, v1 offset:188
	v_readfirstlane_b32 s11, v0
	s_waitcnt lgkmcnt(0)
	v_readfirstlane_b32 s15, v3
	v_readfirstlane_b32 s12, v4
	v_lshlrev_b32_e32 v3, 4, v205
	v_and_b32_e32 v4, 32, v205
	v_bitop3_b32 v4, v3, v4, 48 bitop3:0x6c
	v_add_u32_e32 v3, 0x2000, v3
	v_readfirstlane_b32 s13, v5
	s_add_u32 s42, s12, 0x4e80000
	v_bfe_u32 v5, v205, 2, 4
	v_lshrrev_b32_e32 v6, 1, v205
	v_lshrrev_b32_e32 v4, 1, v4
	v_lshrrev_b32_e32 v3, 7, v3
	s_addc_u32 s43, s13, 0
	v_and_or_b32 v4, v6, 32, v4
	v_lshrrev_b32_e32 v6, 3, v205
	v_and_or_b32 v3, v3, s0, v5
	s_add_u32 s44, s12, 0x13e74000
	v_and_or_b32 v6, v6, s0, v5
	v_mul_u32_u24_e32 v3, 0xb00, v3
	s_addc_u32 s45, s13, 0
	v_mul_u32_u24_e32 v6, 0xb00, v6
	v_or_b32_e32 v3, v3, v4
	v_or_b32_e32 v6, v6, v4
	v_lshlrev_b32_e32 v198, 1, v3
	v_ashrrev_i32_e32 v3, 8, v205
	v_and_b32_e32 v4, 15, v205
	v_bfe_u32 v5, v205, 4, 2
	s_and_b64 s[2:3], s[70:71], exec
	v_lshlrev_b32_e32 v196, 1, v6
	s_cselect_b32 s55, 0, s73
	v_lshlrev_b32_e32 v6, 4, v5
	v_lshlrev_b32_e32 v7, 6, v4
	v_lshlrev_b32_e32 v8, 2, v205
	v_lshl_or_b32 v229, v3, 6, v4
	v_lshlrev_b32_e32 v4, 6, v205
	s_lshl_b32 s56, s55, 10
	v_and_b32_e32 v8, 32, v8
	v_and_or_b32 v4, v4, s8, v6
	s_movk_i32 s8, 0x400
	v_xad_u32 v4, v4, v8, s8
	s_lshl_b64 s[8:9], s[56:57], 2
	s_add_u32 s16, s10, s8
	s_addc_u32 s17, s11, s9
	s_add_u32 s18, s12, 0x280000
	v_ashrrev_i32_e32 v0, 6, v205
	s_addc_u32 s19, s13, 0
	v_readfirstlane_b32 s14, v2
	v_and_b32_e32 v2, 3, v0
	s_add_u32 s20, s12, 0xa80000
	v_lshlrev_b32_e32 v228, 10, v0
	v_lshlrev_b32_e32 v0, 12, v2
	v_bitop3_b32 v7, v6, v8, v7 bitop3:0x36
	v_lshlrev_b32_e32 v200, 5, v2
	v_lshlrev_b32_e32 v2, 13, v3
	s_addc_u32 s21, s13, 0
	v_cmp_eq_u32_e64 s[2:3], 1, v3
	v_add_u32_e32 v9, s33, v7
	v_add_u32_e32 v10, s52, v7
	v_add_u32_e32 v11, s53, v7
	v_add_u32_e32 v12, s34, v7
	v_lshlrev_b32_e32 v202, 2, v5
	v_cmp_eq_u32_e64 s[6:7], 0, v5
	v_add_u32_e32 v3, 0x400, v7
	v_or_b32_e32 v5, 0x800, v2
	v_or_b32_e32 v6, 0x1000, v2
	v_or_b32_e32 v7, 0x1800, v2
	s_add_u32 s22, s12, 0x12b10000
	v_cmp_lt_i32_e64 s[0:1], s49, v205
	s_mul_i32 s55, s55, 9
	v_cmp_gt_u32_e64 s[4:5], s47, v205
	v_or_b32_e32 v204, v200, v202
	v_mov_b32_e32 v197, v1
	v_mov_b32_e32 v199, v1
	s_addc_u32 s23, s13, 0
	v_add_u32_e32 v230, v9, v0
	v_add_u32_e32 v231, v3, v2
	v_add_u32_e32 v232, v4, v5
	v_add_u32_e32 v233, v4, v6
	v_add_u32_e32 v234, v4, v7
	v_add_u32_e32 v235, v10, v0
	v_add_u32_e32 v236, v11, v0
	v_add_u32_e32 v237, v12, v0
	s_branch .LBB0_1613

.LBB0_1634:
	s_mul_hi_i32 s10, s56, 0x78787879
	s_lshr_b32 s11, s10, 31
	s_ashr_i32 s10, s10, 11
	s_add_i32 s10, s10, s11
	s_mul_i32 s11, s10, 0xffffef00
	s_add_i32 s11, s11, s56
	s_cmpk_gt_i32 s11, 0xff
	s_waitcnt lgkmcnt(0)
	v_add_u32_sdwa v2, s24, v205 dst_sel:DWORD dst_unused:UNUSED_PAD src0_sel:DWORD src1_sel:BYTE_0
	s_cselect_b32 s25, s10, 8
	v_ashrrev_i32_e32 v3, 31, v2
	s_and_saveexec_b64 s[10:11], s[0:1]
	s_xor_b64 s[10:11], exec, s[10:11]
	s_cbranch_execz .LBB0_1636
	s_add_i32 s26, s25, s55
	s_mul_hi_i32 s27, s26, 0x6000
	s_mulk_i32 s26, 0x6000
	s_add_u32 s26, s12, s26
	s_addc_u32 s27, s13, s27
	v_lshlrev_b64 v[2:3], 2, v[2:3]
	v_lshl_add_u64 v[4:5], s[16:17], 0, v[2:3]
	v_lshl_add_u64 v[2:3], s[26:27], 0, v[2:3]
	v_add_co_u32_e32 v2, vcc, 0x1000, v2
	global_load_dword v0, v[4:5], off
	s_nop 0
	v_addc_co_u32_e32 v3, vcc, 0, v3, vcc
	global_load_dword v6, v[2:3], off
.LBB0_1636:
	s_andn2_saveexec_b64 s[10:11], s[10:11]
	s_cbranch_execz .LBB0_1638
	v_readlane_b32 s26, v254, 44
	s_add_i32 s25, s25, s26
	s_mul_hi_i32 s27, s25, 0x6000
	s_mulk_i32 s25, 0x6000
	s_add_u32 s26, s12, s25
	s_addc_u32 s27, s13, s27
	v_lshl_add_u64 v[2:3], v[2:3], 2, s[26:27]
	v_add_co_u32_e32 v2, vcc, 0x5000, v2
	s_nop 1
	v_addc_co_u32_e32 v3, vcc, 0, v3, vcc
	global_load_dword v0, v[2:3], off
	v_mov_b32_e32 v6, 0
.LBB0_1638:
	s_or_b64 exec, exec, s[10:11]
	s_lshl_b32 s10, s54, 12
	s_and_b32 s10, s10, 0x1000
	s_add_i32 s58, s10, 0x400
	s_add_i32 s58, s58, 0x20000
	s_mul_i32 s70, s24, 0x1600
	s_mul_hi_i32 s59, s24, 0x1600
	s_add_u32 s10, s44, s70
	v_add_u32_e32 v238, s33, v228
	v_lshl_add_u32 v7, v205, 2, s58
	s_addc_u32 s11, s45, s59
	v_readfirstlane_b32 s25, v238
	v_add_u32_e32 v239, 0x2000, v238
	s_mul_i32 s76, s56, 0x1600
	s_waitcnt lgkmcnt(0)
	v_lshl_add_u64 v[2:3], s[10:11], 0, v[196:197]
	s_mov_b32 m0, s25
	v_readfirstlane_b32 s25, v239
	s_mul_hi_i32 s71, s56, 0x1600
	s_add_u32 s28, s42, s76
	v_add_u32_e32 v240, 0x400, v228
	global_load_lds_dwordx4 v[2:3], off
	v_lshl_add_u64 v[2:3], s[10:11], 0, v[198:199]
	s_mov_b32 m0, s25
	s_addc_u32 s29, s43, s71
	v_readfirstlane_b32 s25, v240
	v_add_u32_e32 v241, 0x2000, v240
	global_load_lds_dwordx4 v[2:3], off
	v_lshl_add_u64 v[2:3], s[28:29], 0, v[196:197]
	s_mov_b32 m0, s25
	v_readfirstlane_b32 s25, v241
	global_load_lds_dwordx4 v[2:3], off
	s_mov_b32 m0, s25
	s_add_i32 s25, s24, 0x80
	s_add_i32 s91, s70, 0xb0000
	s_mul_hi_i32 s77, s25, 0x1600
	s_add_u32 s30, s44, s91
	v_add_u32_e32 v242, s52, v228
	v_lshl_add_u64 v[2:3], s[28:29], 0, v[198:199]
	s_addc_u32 s31, s45, s77
	v_readfirstlane_b32 s25, v242
	v_add_u32_e32 v243, 0x2000, v242
	global_load_lds_dwordx4 v[2:3], off
	v_lshl_add_u64 v[2:3], s[30:31], 0, v[196:197]
	s_mov_b32 m0, s25
	v_readfirstlane_b32 s25, v243
	global_load_lds_dwordx4 v[2:3], off
	s_mov_b32 m0, s25
	s_add_i32 s25, s56, 0x80
	s_add_i32 s95, s76, 0xb0000
	s_mul_hi_i32 s94, s25, 0x1600
	s_add_u32 s26, s42, s95
	v_add_u32_e32 v244, 0x4000, v240
	v_lshl_add_u64 v[2:3], s[30:31], 0, v[198:199]
	s_addc_u32 s27, s43, s94
	v_readfirstlane_b32 s25, v244
	v_add_u32_e32 v245, 0x6000, v240
	global_load_lds_dwordx4 v[2:3], off
	v_lshl_add_u64 v[2:3], s[26:27], 0, v[196:197]
	s_mov_b32 m0, s25
	v_readfirstlane_b32 s25, v245
	global_load_lds_dwordx4 v[2:3], off
	v_lshl_add_u64 v[2:3], s[26:27], 0, v[198:199]
	s_mov_b32 m0, s25
	s_nop 0
	global_load_lds_dwordx4 v[2:3], off
	s_waitcnt vmcnt(8)
	v_add_f32_e32 v6, 1.0, v6
	v_mul_f32_e32 v0, v0, v6
	ds_write_b32 v7, v0 offset:1024
	s_waitcnt lgkmcnt(0)
	s_barrier
	s_and_saveexec_b64 s[40:41], s[2:3]
	s_cbranch_execz .LBB0_1640
	s_barrier
